# two P2 queues (128 SA-first) + P0 H / transposed-weight stores written through (sc0 sc1) so the seam-0 barrier L2 write-back has little to flush
# speedup vs baseline: 1.0279x; 1.0279x over previous
.LBB0_9:
	s_or_b64 exec, exec, s[2:3]
	v_lshlrev_b32_e32 v120, 6, v17
	v_or_b32_e32 v53, v120, v1
	v_ashrrev_i32_e32 v17, 31, v16
	v_lshl_add_u64 v[16:17], v[16:17], 2, v[14:15]
	v_or_b32_e32 v56, 4, v53
	v_or_b32_e32 v62, 8, v53
	v_or_b32_e32 v64, 12, v53
	v_or_b32_e32 v70, 16, v53
	v_or_b32_e32 v72, 20, v53
	v_or_b32_e32 v78, 24, v53
	v_or_b32_e32 v80, 28, v53
	v_or_b32_e32 v86, 32, v53
	v_or_b32_e32 v88, 36, v53
	v_or_b32_e32 v99, 44, v53
	v_mad_i64_i32 v[54:55], s[2:3], v53, s25, v[16:17]
	v_mad_i64_i32 v[58:59], s[2:3], v56, s25, v[16:17]
	v_mad_i64_i32 v[62:63], s[2:3], v62, s25, v[16:17]
	v_mad_i64_i32 v[66:67], s[2:3], v64, s25, v[16:17]
	v_mad_i64_i32 v[70:71], s[2:3], v70, s25, v[16:17]
	v_mad_i64_i32 v[74:75], s[2:3], v72, s25, v[16:17]
	v_mad_i64_i32 v[78:79], s[2:3], v78, s25, v[16:17]
	v_mad_i64_i32 v[82:83], s[2:3], v80, s25, v[16:17]
	v_mad_i64_i32 v[86:87], s[2:3], v86, s25, v[16:17]
	v_mad_i64_i32 v[90:91], s[2:3], v88, s25, v[16:17]
	v_mad_i64_i32 v[100:101], s[2:3], v99, s25, v[16:17]
	v_or_b32_e32 v99, 48, v53
	global_load_dwordx4 v[54:57], v[54:55], off nt
	s_nop 0
	global_load_dwordx4 v[58:61], v[58:59], off nt
	s_nop 0
	global_load_dwordx4 v[62:65], v[62:63], off nt
	s_nop 0
	global_load_dwordx4 v[66:69], v[66:67], off nt
	s_nop 0
	global_load_dwordx4 v[70:73], v[70:71], off nt
	s_nop 0
	global_load_dwordx4 v[74:77], v[74:75], off nt
	s_nop 0
	global_load_dwordx4 v[78:81], v[78:79], off nt
	s_nop 0
	global_load_dwordx4 v[82:85], v[82:83], off nt
	s_nop 0
	global_load_dwordx4 v[86:89], v[86:87], off nt
	s_nop 0
	global_load_dwordx4 v[90:93], v[90:91], off nt
	v_mad_i64_i32 v[104:105], s[2:3], v99, s25, v[16:17]
	global_load_dwordx4 v[100:103], v[100:101], off nt
	v_or_b32_e32 v99, 52, v53
	global_load_dwordx4 v[104:107], v[104:105], off nt
	v_mad_i64_i32 v[108:109], s[2:3], v99, s25, v[16:17]
	global_load_dwordx4 v[108:111], v[108:109], off nt
	v_or_b32_e32 v99, 56, v53
	v_mad_i64_i32 v[112:113], s[2:3], v99, s25, v[16:17]
	v_or_b32_e32 v94, 40, v53
	global_load_dwordx4 v[112:115], v[112:113], off nt
	v_or_b32_e32 v53, 60, v53
	v_mad_i64_i32 v[94:95], s[2:3], v94, s25, v[16:17]
	v_mad_i64_i32 v[16:17], s[2:3], v53, s25, v[16:17]
	global_load_dwordx4 v[94:97], v[94:95], off nt
	v_add_u32_e32 v53, 0x400, v20
	global_load_dwordx4 v[116:119], v[16:17], off nt
	v_add_u32_e32 v16, 0x2cb8, v18
	v_ashrrev_i32_e32 v121, 31, v120
	s_waitcnt vmcnt(15)
	ds_write2_b32 v18, v54, v55 offset1:1
	ds_write2_b32 v18, v56, v57 offset0:2 offset1:3
	s_waitcnt vmcnt(14)
	ds_write2_b32 v31, v58, v59 offset1:1
	ds_write2_b32 v32, v60, v61 offset1:1
	s_waitcnt vmcnt(13)
	ds_write2_b32 v33, v62, v63 offset1:1
	ds_write2_b32 v34, v64, v65 offset1:1
	s_waitcnt vmcnt(12)
	ds_write2_b32 v35, v66, v67 offset1:1
	ds_write2_b32 v36, v68, v69 offset1:1
	s_waitcnt vmcnt(11)
	ds_write2_b32 v37, v70, v71 offset1:1
	ds_write2_b32 v38, v72, v73 offset1:1
	s_waitcnt vmcnt(10)
	ds_write2_b32 v39, v74, v75 offset1:1
	ds_write2_b32 v40, v76, v77 offset1:1
	s_waitcnt vmcnt(9)
	ds_write2_b32 v41, v78, v79 offset1:1
	ds_write2_b32 v42, v80, v81 offset1:1
	s_waitcnt vmcnt(8)
	ds_write2_b32 v43, v82, v83 offset1:1
	ds_write2_b32 v44, v84, v85 offset1:1
	s_waitcnt vmcnt(7)
	ds_write2_b32 v45, v86, v87 offset1:1
	ds_write2_b32 v46, v88, v89 offset1:1
	s_waitcnt vmcnt(6)
	ds_write2_b32 v47, v90, v91 offset1:1
	ds_write2_b32 v48, v92, v93 offset1:1
	s_waitcnt vmcnt(1)
	ds_write2_b32 v49, v94, v95 offset1:1
	ds_write2_b32 v50, v96, v97 offset1:1
	ds_write2_b32 v51, v100, v101 offset1:1
	v_lshl_add_u64 v[58:59], v[120:121], 1, v[8:9]
	ds_write2_b32 v16, v102, v103 offset1:1
	v_add_u32_e32 v16, 0x30c0, v18
	ds_write2_b32 v16, v104, v105 offset1:1
	v_add_u32_e32 v16, 0x30c8, v18
	ds_write2_b32 v16, v106, v107 offset1:1
	v_add_u32_e32 v16, 0x34d0, v18
	ds_write2_b32 v16, v108, v109 offset1:1
	v_add_u32_e32 v16, 0x34d8, v18
	ds_write2_b32 v16, v110, v111 offset1:1
	v_add_u32_e32 v16, 0x38e0, v18
	ds_write2_b32 v16, v112, v113 offset1:1
	v_add_u32_e32 v16, 0x38e8, v18
	ds_write2_b32 v16, v114, v115 offset1:1
	v_add_u32_e32 v16, 0x3cf0, v18
	s_waitcnt vmcnt(0)
	ds_write2_b32 v16, v116, v117 offset1:1
	v_add_u32_e32 v16, 0x3cf8, v18
	ds_write2_b32 v16, v118, v119 offset1:1
	s_waitcnt lgkmcnt(0)
	ds_read2_b32 v[16:17], v20 offset1:65
	s_waitcnt lgkmcnt(0)
	v_cvt_pk_bf16_f32 v54, v16, v17
	ds_read2_b32 v[16:17], v20 offset0:130 offset1:195
	s_waitcnt lgkmcnt(0)
	v_cvt_pk_bf16_f32 v55, v16, v17
	ds_read2_b32 v[16:17], v53 offset0:4 offset1:69
	s_waitcnt lgkmcnt(0)
	v_cvt_pk_bf16_f32 v56, v16, v17
	ds_read2_b32 v[16:17], v53 offset0:134 offset1:199
	s_waitcnt lgkmcnt(0)
	v_cvt_pk_bf16_f32 v57, v16, v17
	v_add3_u32 v16, v19, v28, v2
	v_ashrrev_i32_e32 v17, 31, v16
	v_lshlrev_b64 v[62:63], 12, v[16:17]
	v_lshl_add_u64 v[62:63], v[58:59], 0, v[62:63]
	ds_read2_b32 v[60:61], v20 offset0:8 offset1:73
	global_store_dwordx4 v[62:63], v[54:57], off sc0 sc1
	s_waitcnt lgkmcnt(0)
	s_nop 0
	v_cvt_pk_bf16_f32 v54, v60, v61
	ds_read2_b32 v[56:57], v20 offset0:138 offset1:203
	s_waitcnt lgkmcnt(0)
	v_cvt_pk_bf16_f32 v55, v56, v57
	ds_read2_b32 v[56:57], v53 offset0:12 offset1:77
	s_waitcnt lgkmcnt(0)
	v_cvt_pk_bf16_f32 v56, v56, v57
	ds_read2_b32 v[60:61], v53 offset0:142 offset1:207
	s_waitcnt lgkmcnt(0)
	v_cvt_pk_bf16_f32 v57, v60, v61
	v_add_u32_e32 v60, 8, v16
	v_ashrrev_i32_e32 v61, 31, v60
	v_lshlrev_b64 v[60:61], 12, v[60:61]
	ds_read2_b32 v[62:63], v20 offset0:16 offset1:81
	v_lshl_add_u64 v[60:61], v[58:59], 0, v[60:61]
	global_store_dwordx4 v[60:61], v[54:57], off sc0 sc1
	s_waitcnt lgkmcnt(0)
	s_nop 0
	v_cvt_pk_bf16_f32 v54, v62, v63
	v_add_u32_e32 v62, 16, v16
	v_ashrrev_i32_e32 v63, 31, v62
	ds_read2_b32 v[56:57], v20 offset0:146 offset1:211
	v_lshlrev_b64 v[62:63], 12, v[62:63]
	s_waitcnt lgkmcnt(0)
	v_cvt_pk_bf16_f32 v55, v56, v57
	ds_read2_b32 v[56:57], v53 offset0:20 offset1:85
	v_lshl_add_u64 v[62:63], v[58:59], 0, v[62:63]
	s_waitcnt lgkmcnt(0)
	v_cvt_pk_bf16_f32 v56, v56, v57
	ds_read2_b32 v[60:61], v53 offset0:150 offset1:215
	s_waitcnt lgkmcnt(0)
	v_cvt_pk_bf16_f32 v57, v60, v61
	global_store_dwordx4 v[62:63], v[54:57], off sc0 sc1
	v_add_u32_e32 v62, 24, v16
	v_ashrrev_i32_e32 v63, 31, v62
	ds_read2_b32 v[60:61], v20 offset0:24 offset1:89
	s_waitcnt lgkmcnt(0)
	v_cvt_pk_bf16_f32 v54, v60, v61
	ds_read2_b32 v[56:57], v20 offset0:154 offset1:219
	v_lshlrev_b64 v[62:63], 12, v[62:63]
	s_waitcnt lgkmcnt(0)
	v_cvt_pk_bf16_f32 v55, v56, v57
	ds_read2_b32 v[56:57], v53 offset0:28 offset1:93
	v_lshl_add_u64 v[62:63], v[58:59], 0, v[62:63]
	s_waitcnt lgkmcnt(0)
	v_cvt_pk_bf16_f32 v56, v56, v57
	ds_read2_b32 v[60:61], v53 offset0:158 offset1:223
	s_waitcnt lgkmcnt(0)
	v_cvt_pk_bf16_f32 v57, v60, v61
	global_store_dwordx4 v[62:63], v[54:57], off sc0 sc1
	v_add_u32_e32 v62, 32, v16
	v_ashrrev_i32_e32 v63, 31, v62
	ds_read2_b32 v[60:61], v20 offset0:32 offset1:97
	s_waitcnt lgkmcnt(0)
	v_cvt_pk_bf16_f32 v54, v60, v61
	ds_read2_b32 v[56:57], v20 offset0:162 offset1:227
	v_lshlrev_b64 v[62:63], 12, v[62:63]
	s_waitcnt lgkmcnt(0)
	v_cvt_pk_bf16_f32 v55, v56, v57
	ds_read2_b32 v[56:57], v53 offset0:36 offset1:101
	v_lshl_add_u64 v[62:63], v[58:59], 0, v[62:63]
	s_waitcnt lgkmcnt(0)
	v_cvt_pk_bf16_f32 v56, v56, v57
	ds_read2_b32 v[60:61], v53 offset0:166 offset1:231
	s_waitcnt lgkmcnt(0)
	v_cvt_pk_bf16_f32 v57, v60, v61
	global_store_dwordx4 v[62:63], v[54:57], off sc0 sc1
	v_add_u32_e32 v62, 40, v16
	v_ashrrev_i32_e32 v63, 31, v62
	ds_read2_b32 v[60:61], v20 offset0:40 offset1:105
	s_waitcnt lgkmcnt(0)
	v_cvt_pk_bf16_f32 v54, v60, v61
	ds_read2_b32 v[56:57], v20 offset0:170 offset1:235
	v_lshlrev_b64 v[62:63], 12, v[62:63]
	s_waitcnt lgkmcnt(0)
	v_cvt_pk_bf16_f32 v55, v56, v57
	ds_read2_b32 v[56:57], v53 offset0:44 offset1:109
	v_lshl_add_u64 v[62:63], v[58:59], 0, v[62:63]
	s_waitcnt lgkmcnt(0)
	v_cvt_pk_bf16_f32 v56, v56, v57
	ds_read2_b32 v[60:61], v53 offset0:174 offset1:239
	s_waitcnt lgkmcnt(0)
	v_cvt_pk_bf16_f32 v57, v60, v61
	global_store_dwordx4 v[62:63], v[54:57], off sc0 sc1
	v_add_u32_e32 v62, 48, v16
	ds_read2_b32 v[60:61], v20 offset0:48 offset1:113
	s_waitcnt lgkmcnt(0)
	v_cvt_pk_bf16_f32 v54, v60, v61
	ds_read2_b32 v[56:57], v20 offset0:178 offset1:243
	v_ashrrev_i32_e32 v63, 31, v62
	s_waitcnt lgkmcnt(0)
	v_cvt_pk_bf16_f32 v55, v56, v57
	ds_read2_b32 v[56:57], v53 offset0:52 offset1:117
	v_lshlrev_b64 v[62:63], 12, v[62:63]
	v_add_u32_e32 v16, 56, v16
	s_waitcnt lgkmcnt(0)
	v_cvt_pk_bf16_f32 v56, v56, v57
	ds_read2_b32 v[60:61], v53 offset0:182 offset1:247
	s_waitcnt lgkmcnt(0)
	v_cvt_pk_bf16_f32 v57, v60, v61
	v_lshl_add_u64 v[62:63], v[58:59], 0, v[62:63]
	v_ashrrev_i32_e32 v17, 31, v16
	ds_read2_b32 v[60:61], v20 offset0:56 offset1:121
	global_store_dwordx4 v[62:63], v[54:57], off sc0 sc1
	v_lshlrev_b64 v[16:17], 12, v[16:17]
	v_lshl_add_u64 v[16:17], v[58:59], 0, v[16:17]
	s_waitcnt lgkmcnt(0)
	v_cvt_pk_bf16_f32 v54, v60, v61
	ds_read2_b32 v[56:57], v20 offset0:186 offset1:251
	s_waitcnt lgkmcnt(0)
	v_cvt_pk_bf16_f32 v55, v56, v57
	ds_read2_b32 v[56:57], v53 offset0:60 offset1:125
	s_waitcnt lgkmcnt(0)
	v_cvt_pk_bf16_f32 v56, v56, v57
	ds_read2_b32 v[60:61], v53 offset0:190 offset1:255
	s_waitcnt lgkmcnt(0)
	v_cvt_pk_bf16_f32 v57, v60, v61
	global_store_dwordx4 v[16:17], v[54:57], off sc0 sc1
	s_waitcnt lgkmcnt(0)

.LBB0_11:
	v_cmp_lt_i32_e32 vcc, s17, v52
	s_and_saveexec_b64 s[0:1], vcc
	s_xor_b64 s[14:15], exec, s[0:1]
	s_cbranch_execz .LBB0_17
	v_cmp_lt_u32_e32 vcc, s18, v52
	s_and_saveexec_b64 s[0:1], vcc
	s_xor_b64 s[0:1], exec, s[0:1]
	s_cbranch_execz .LBB0_14
	v_and_b32_e32 v2, 0x7fffffc0, v29
	v_add_u32_e32 v16, 0xffff6800, v2
	v_and_b32_e32 v53, 0x1c0, v28
	v_or_b32_e32 v116, v16, v1
	v_lshlrev_b32_e32 v2, 2, v53
	v_lshl_add_u64 v[118:119], v[10:11], 0, v[2:3]
	v_or_b32_e32 v2, 4, v116
	v_lshlrev_b64 v[56:57], 11, v[2:3]
	v_or_b32_e32 v2, 8, v116
	v_lshlrev_b64 v[62:63], 11, v[2:3]
	v_or_b32_e32 v2, 12, v116
	v_lshlrev_b64 v[64:65], 11, v[2:3]
	v_or_b32_e32 v2, 16, v116
	v_lshlrev_b64 v[70:71], 11, v[2:3]
	v_or_b32_e32 v2, 20, v116
	v_lshlrev_b64 v[72:73], 11, v[2:3]
	v_or_b32_e32 v2, 24, v116
	v_lshlrev_b64 v[78:79], 11, v[2:3]
	v_or_b32_e32 v2, 28, v116
	v_lshlrev_b64 v[80:81], 11, v[2:3]
	v_or_b32_e32 v2, 32, v116
	v_lshlrev_b64 v[86:87], 11, v[2:3]
	v_or_b32_e32 v2, 36, v116
	v_lshlrev_b64 v[88:89], 11, v[2:3]
	v_or_b32_e32 v2, 40, v116
	v_lshlrev_b64 v[94:95], 11, v[2:3]
	v_or_b32_e32 v2, 44, v116
	v_mov_b32_e32 v117, v3
	v_lshlrev_b64 v[96:97], 11, v[2:3]
	v_or_b32_e32 v2, 48, v116
	v_lshlrev_b64 v[54:55], 11, v[116:117]
	v_lshlrev_b64 v[104:105], 11, v[2:3]
	v_or_b32_e32 v2, 52, v116
	v_lshl_add_u64 v[54:55], v[118:119], 0, v[54:55]
	v_lshl_add_u64 v[58:59], v[118:119], 0, v[56:57]
	v_lshl_add_u64 v[62:63], v[118:119], 0, v[62:63]
	v_lshl_add_u64 v[66:67], v[118:119], 0, v[64:65]
	v_lshl_add_u64 v[70:71], v[118:119], 0, v[70:71]
	v_lshl_add_u64 v[74:75], v[118:119], 0, v[72:73]
	v_lshl_add_u64 v[78:79], v[118:119], 0, v[78:79]
	v_lshl_add_u64 v[82:83], v[118:119], 0, v[80:81]
	v_lshl_add_u64 v[86:87], v[118:119], 0, v[86:87]
	v_lshl_add_u64 v[90:91], v[118:119], 0, v[88:89]
	v_lshl_add_u64 v[94:95], v[118:119], 0, v[94:95]
	v_lshl_add_u64 v[100:101], v[118:119], 0, v[96:97]
	v_lshlrev_b64 v[108:109], 11, v[2:3]
	global_load_dwordx4 v[54:57], v[54:55], off nt
	s_nop 0
	global_load_dwordx4 v[58:61], v[58:59], off nt
	s_nop 0
	global_load_dwordx4 v[62:65], v[62:63], off nt
	s_nop 0
	global_load_dwordx4 v[66:69], v[66:67], off nt
	s_nop 0
	global_load_dwordx4 v[70:73], v[70:71], off nt
	s_nop 0
	global_load_dwordx4 v[74:77], v[74:75], off nt
	s_nop 0
	global_load_dwordx4 v[78:81], v[78:79], off nt
	s_nop 0
	global_load_dwordx4 v[82:85], v[82:83], off nt
	s_nop 0
	global_load_dwordx4 v[86:89], v[86:87], off nt
	s_nop 0
	global_load_dwordx4 v[90:93], v[90:91], off nt
	s_nop 0
	global_load_dwordx4 v[94:97], v[94:95], off nt
	s_nop 0
	global_load_dwordx4 v[100:103], v[100:101], off nt
	v_lshl_add_u64 v[104:105], v[118:119], 0, v[104:105]
	v_lshl_add_u64 v[108:109], v[118:119], 0, v[108:109]
	v_or_b32_e32 v2, 56, v116
	global_load_dwordx4 v[104:107], v[104:105], off nt
	v_lshlrev_b64 v[112:113], 11, v[2:3]
	global_load_dwordx4 v[108:111], v[108:109], off nt
	v_lshl_add_u64 v[112:113], v[118:119], 0, v[112:113]
	v_or_b32_e32 v2, 60, v116
	global_load_dwordx4 v[112:115], v[112:113], off nt
	v_lshlrev_b64 v[116:117], 11, v[2:3]
	v_lshl_add_u64 v[116:117], v[118:119], 0, v[116:117]
	global_load_dwordx4 v[116:119], v[116:117], off nt
	v_add_u32_e32 v2, 0x2cb8, v18
	v_add_u32_e32 v17, 0x30c0, v18
	v_add_u32_e32 v99, 0x30c8, v18
	s_waitcnt vmcnt(15)
	ds_write2_b32 v18, v54, v55 offset1:1
	ds_write2_b32 v18, v56, v57 offset0:2 offset1:3
	s_waitcnt vmcnt(14)
	ds_write2_b32 v31, v58, v59 offset1:1
	ds_write2_b32 v32, v60, v61 offset1:1
	s_waitcnt vmcnt(13)
	ds_write2_b32 v33, v62, v63 offset1:1
	ds_write2_b32 v34, v64, v65 offset1:1
	s_waitcnt vmcnt(12)
	ds_write2_b32 v35, v66, v67 offset1:1
	ds_write2_b32 v36, v68, v69 offset1:1
	s_waitcnt vmcnt(11)
	ds_write2_b32 v37, v70, v71 offset1:1
	ds_write2_b32 v38, v72, v73 offset1:1
	s_waitcnt vmcnt(10)
	ds_write2_b32 v39, v74, v75 offset1:1
	ds_write2_b32 v40, v76, v77 offset1:1
	s_waitcnt vmcnt(9)
	ds_write2_b32 v41, v78, v79 offset1:1
	ds_write2_b32 v42, v80, v81 offset1:1
	s_waitcnt vmcnt(8)
	ds_write2_b32 v43, v82, v83 offset1:1
	ds_write2_b32 v44, v84, v85 offset1:1
	s_waitcnt vmcnt(7)
	ds_write2_b32 v45, v86, v87 offset1:1
	ds_write2_b32 v46, v88, v89 offset1:1
	s_waitcnt vmcnt(6)
	ds_write2_b32 v47, v90, v91 offset1:1
	ds_write2_b32 v48, v92, v93 offset1:1
	s_waitcnt vmcnt(5)
	ds_write2_b32 v49, v94, v95 offset1:1
	ds_write2_b32 v50, v96, v97 offset1:1
	s_waitcnt vmcnt(4)
	ds_write2_b32 v51, v100, v101 offset1:1
	ds_write2_b32 v2, v102, v103 offset1:1
	s_waitcnt vmcnt(3)
	ds_write2_b32 v17, v104, v105 offset1:1
	ds_write2_b32 v99, v106, v107 offset1:1
	v_add_u32_e32 v2, 0x34d0, v18
	v_add_u32_e32 v62, 0x400, v20
	v_mov_b32_e32 v17, v3
	v_lshl_add_u64 v[16:17], v[16:17], 1, v[4:5]
	s_waitcnt vmcnt(2)
	ds_write2_b32 v2, v108, v109 offset1:1
	v_add_u32_e32 v2, 0x34d8, v18
	ds_write2_b32 v2, v110, v111 offset1:1
	v_add_u32_e32 v2, 0x38e0, v18
	s_waitcnt vmcnt(1)
	ds_write2_b32 v2, v112, v113 offset1:1
	v_add_u32_e32 v2, 0x38e8, v18
	ds_write2_b32 v2, v114, v115 offset1:1
	v_add_u32_e32 v2, 0x3cf0, v18
	s_waitcnt vmcnt(0)
	ds_write2_b32 v2, v116, v117 offset1:1
	v_add_u32_e32 v2, 0x3cf8, v18
	ds_write2_b32 v2, v118, v119 offset1:1
	s_waitcnt lgkmcnt(0)
	ds_read2_b32 v[54:55], v20 offset1:65
	s_waitcnt lgkmcnt(0)
	v_cvt_pk_bf16_f32 v54, v54, v55
	ds_read2_b32 v[56:57], v20 offset0:130 offset1:195
	v_or_b32_e32 v2, v53, v19
	s_waitcnt lgkmcnt(0)
	v_cvt_pk_bf16_f32 v55, v56, v57
	ds_read2_b32 v[56:57], v62 offset0:4 offset1:69
	v_lshlrev_b32_e32 v2, 10, v2
	s_waitcnt lgkmcnt(0)
	v_cvt_pk_bf16_f32 v56, v56, v57
	ds_read2_b32 v[58:59], v62 offset0:134 offset1:199
	s_waitcnt lgkmcnt(0)
	v_cvt_pk_bf16_f32 v57, v58, v59
	v_lshl_add_u64 v[60:61], v[16:17], 0, v[2:3]
	ds_read2_b32 v[58:59], v20 offset0:8 offset1:73
	global_store_dwordx4 v[60:61], v[54:57], off sc0 sc1
	v_or_b32_e32 v2, v53, v21
	v_lshlrev_b32_e32 v2, 10, v2
	s_waitcnt lgkmcnt(0)
	v_cvt_pk_bf16_f32 v54, v58, v59
	ds_read2_b32 v[56:57], v20 offset0:138 offset1:203
	s_waitcnt lgkmcnt(0)
	v_cvt_pk_bf16_f32 v55, v56, v57
	ds_read2_b32 v[56:57], v62 offset0:12 offset1:77
	s_waitcnt lgkmcnt(0)
	v_cvt_pk_bf16_f32 v56, v56, v57
	ds_read2_b32 v[58:59], v62 offset0:142 offset1:207
	s_waitcnt lgkmcnt(0)
	v_cvt_pk_bf16_f32 v57, v58, v59
	v_lshl_add_u64 v[60:61], v[16:17], 0, v[2:3]
	ds_read2_b32 v[58:59], v20 offset0:16 offset1:81
	global_store_dwordx4 v[60:61], v[54:57], off sc0 sc1
	v_or_b32_e32 v2, v53, v22
	v_lshlrev_b32_e32 v2, 10, v2
	s_waitcnt lgkmcnt(0)
	v_cvt_pk_bf16_f32 v54, v58, v59
	ds_read2_b32 v[56:57], v20 offset0:146 offset1:211
	s_waitcnt lgkmcnt(0)
	v_cvt_pk_bf16_f32 v55, v56, v57
	ds_read2_b32 v[56:57], v62 offset0:20 offset1:85
	s_waitcnt lgkmcnt(0)
	v_cvt_pk_bf16_f32 v56, v56, v57
	ds_read2_b32 v[58:59], v62 offset0:150 offset1:215
	s_waitcnt lgkmcnt(0)
	v_cvt_pk_bf16_f32 v57, v58, v59
	v_lshl_add_u64 v[60:61], v[16:17], 0, v[2:3]
	ds_read2_b32 v[58:59], v20 offset0:24 offset1:89
	global_store_dwordx4 v[60:61], v[54:57], off sc0 sc1
	v_or_b32_e32 v2, v53, v23
	v_lshlrev_b32_e32 v2, 10, v2
	s_waitcnt lgkmcnt(0)
	v_cvt_pk_bf16_f32 v54, v58, v59
	ds_read2_b32 v[56:57], v20 offset0:154 offset1:219
	s_waitcnt lgkmcnt(0)
	v_cvt_pk_bf16_f32 v55, v56, v57
	ds_read2_b32 v[56:57], v62 offset0:28 offset1:93
	s_waitcnt lgkmcnt(0)
	v_cvt_pk_bf16_f32 v56, v56, v57
	ds_read2_b32 v[58:59], v62 offset0:158 offset1:223
	s_waitcnt lgkmcnt(0)
	v_cvt_pk_bf16_f32 v57, v58, v59
	v_lshl_add_u64 v[60:61], v[16:17], 0, v[2:3]
	ds_read2_b32 v[58:59], v20 offset0:32 offset1:97
	global_store_dwordx4 v[60:61], v[54:57], off sc0 sc1
	v_or_b32_e32 v2, v53, v24
	v_lshlrev_b32_e32 v2, 10, v2
	s_waitcnt lgkmcnt(0)
	v_cvt_pk_bf16_f32 v54, v58, v59
	ds_read2_b32 v[56:57], v20 offset0:162 offset1:227
	s_waitcnt lgkmcnt(0)
	v_cvt_pk_bf16_f32 v55, v56, v57
	ds_read2_b32 v[56:57], v62 offset0:36 offset1:101
	s_waitcnt lgkmcnt(0)
	v_cvt_pk_bf16_f32 v56, v56, v57
	ds_read2_b32 v[58:59], v62 offset0:166 offset1:231
	s_waitcnt lgkmcnt(0)
	v_cvt_pk_bf16_f32 v57, v58, v59
	v_lshl_add_u64 v[60:61], v[16:17], 0, v[2:3]
	ds_read2_b32 v[58:59], v20 offset0:40 offset1:105
	global_store_dwordx4 v[60:61], v[54:57], off sc0 sc1
	v_or_b32_e32 v2, v53, v25
	v_lshlrev_b32_e32 v2, 10, v2
	s_waitcnt lgkmcnt(0)
	v_cvt_pk_bf16_f32 v54, v58, v59
	ds_read2_b32 v[56:57], v20 offset0:170 offset1:235
	s_waitcnt lgkmcnt(0)
	v_cvt_pk_bf16_f32 v55, v56, v57
	ds_read2_b32 v[56:57], v62 offset0:44 offset1:109
	s_waitcnt lgkmcnt(0)
	v_cvt_pk_bf16_f32 v56, v56, v57
	ds_read2_b32 v[58:59], v62 offset0:174 offset1:239
	s_waitcnt lgkmcnt(0)
	v_cvt_pk_bf16_f32 v57, v58, v59
	v_lshl_add_u64 v[60:61], v[16:17], 0, v[2:3]
	ds_read2_b32 v[58:59], v20 offset0:48 offset1:113
	global_store_dwordx4 v[60:61], v[54:57], off sc0 sc1
	v_or_b32_e32 v2, v53, v26
	v_lshlrev_b32_e32 v2, 10, v2
	s_waitcnt lgkmcnt(0)
	v_cvt_pk_bf16_f32 v54, v58, v59
	ds_read2_b32 v[56:57], v20 offset0:178 offset1:243
	s_waitcnt lgkmcnt(0)
	v_cvt_pk_bf16_f32 v55, v56, v57
	ds_read2_b32 v[56:57], v62 offset0:52 offset1:117
	s_waitcnt lgkmcnt(0)
	v_cvt_pk_bf16_f32 v56, v56, v57
	ds_read2_b32 v[58:59], v62 offset0:182 offset1:247
	s_waitcnt lgkmcnt(0)
	v_cvt_pk_bf16_f32 v57, v58, v59
	v_lshl_add_u64 v[60:61], v[16:17], 0, v[2:3]
	v_or_b32_e32 v2, v53, v27
	ds_read2_b32 v[58:59], v20 offset0:56 offset1:121
	global_store_dwordx4 v[60:61], v[54:57], off sc0 sc1
	v_lshlrev_b32_e32 v2, 10, v2
	v_lshl_add_u64 v[16:17], v[16:17], 0, v[2:3]
	s_waitcnt lgkmcnt(0)
	v_cvt_pk_bf16_f32 v54, v58, v59
	ds_read2_b32 v[56:57], v20 offset0:186 offset1:251
	s_waitcnt lgkmcnt(0)
	v_cvt_pk_bf16_f32 v55, v56, v57
	ds_read2_b32 v[56:57], v62 offset0:60 offset1:125
	s_waitcnt lgkmcnt(0)
	v_cvt_pk_bf16_f32 v56, v56, v57
	ds_read2_b32 v[58:59], v62 offset0:190 offset1:255
	s_waitcnt lgkmcnt(0)
	v_cvt_pk_bf16_f32 v57, v58, v59
	global_store_dwordx4 v[16:17], v[54:57], off sc0 sc1
	s_waitcnt lgkmcnt(0)
.LBB0_14:
	s_andn2_saveexec_b64 s[0:1], s[0:1]
	s_cbranch_execz .LBB0_16
	v_and_b32_e32 v2, 0x3fc0, v30
	v_add_u32_e32 v16, 0xffffe200, v2
	v_and_b32_e32 v53, 0x7c0, v28
	v_or_b32_e32 v116, v16, v1
	v_lshlrev_b32_e32 v2, 2, v53
	v_lshl_add_u64 v[118:119], v[12:13], 0, v[2:3]
	v_or_b32_e32 v2, 4, v116
	v_lshlrev_b64 v[56:57], 13, v[2:3]
	v_or_b32_e32 v2, 8, v116
	v_lshlrev_b64 v[62:63], 13, v[2:3]
	v_or_b32_e32 v2, 12, v116
	v_lshlrev_b64 v[64:65], 13, v[2:3]
	v_or_b32_e32 v2, 16, v116
	v_lshlrev_b64 v[70:71], 13, v[2:3]
	v_or_b32_e32 v2, 20, v116
	v_lshlrev_b64 v[72:73], 13, v[2:3]
	v_or_b32_e32 v2, 24, v116
	v_lshlrev_b64 v[78:79], 13, v[2:3]
	v_or_b32_e32 v2, 28, v116
	v_lshlrev_b64 v[80:81], 13, v[2:3]
	v_or_b32_e32 v2, 32, v116
	v_lshlrev_b64 v[86:87], 13, v[2:3]
	v_or_b32_e32 v2, 36, v116
	v_lshlrev_b64 v[88:89], 13, v[2:3]
	v_or_b32_e32 v2, 40, v116
	v_lshlrev_b64 v[94:95], 13, v[2:3]
	v_or_b32_e32 v2, 44, v116
	v_mov_b32_e32 v117, v3
	v_lshlrev_b64 v[96:97], 13, v[2:3]
	v_or_b32_e32 v2, 48, v116
	v_lshlrev_b64 v[54:55], 13, v[116:117]
	v_lshlrev_b64 v[104:105], 13, v[2:3]
	v_or_b32_e32 v2, 52, v116
	v_lshl_add_u64 v[54:55], v[118:119], 0, v[54:55]
	v_lshl_add_u64 v[58:59], v[118:119], 0, v[56:57]
	v_lshl_add_u64 v[62:63], v[118:119], 0, v[62:63]
	v_lshl_add_u64 v[66:67], v[118:119], 0, v[64:65]
	v_lshl_add_u64 v[70:71], v[118:119], 0, v[70:71]
	v_lshl_add_u64 v[74:75], v[118:119], 0, v[72:73]
	v_lshl_add_u64 v[78:79], v[118:119], 0, v[78:79]
	v_lshl_add_u64 v[82:83], v[118:119], 0, v[80:81]
	v_lshl_add_u64 v[86:87], v[118:119], 0, v[86:87]
	v_lshl_add_u64 v[90:91], v[118:119], 0, v[88:89]
	v_lshlrev_b64 v[108:109], 13, v[2:3]
	global_load_dwordx4 v[54:57], v[54:55], off nt
	s_nop 0
	global_load_dwordx4 v[58:61], v[58:59], off nt
	s_nop 0
	global_load_dwordx4 v[62:65], v[62:63], off nt
	s_nop 0
	global_load_dwordx4 v[66:69], v[66:67], off nt
	s_nop 0
	global_load_dwordx4 v[70:73], v[70:71], off nt
	s_nop 0
	global_load_dwordx4 v[74:77], v[74:75], off nt
	s_nop 0
	global_load_dwordx4 v[78:81], v[78:79], off nt
	s_nop 0
	global_load_dwordx4 v[82:85], v[82:83], off nt
	s_nop 0
	global_load_dwordx4 v[86:89], v[86:87], off nt
	s_nop 0
	global_load_dwordx4 v[90:93], v[90:91], off nt
	v_lshl_add_u64 v[104:105], v[118:119], 0, v[104:105]
	v_lshl_add_u64 v[108:109], v[118:119], 0, v[108:109]
	v_or_b32_e32 v2, 56, v116
	global_load_dwordx4 v[104:107], v[104:105], off nt
	v_lshlrev_b64 v[112:113], 13, v[2:3]
	global_load_dwordx4 v[108:111], v[108:109], off nt
	v_lshl_add_u64 v[112:113], v[118:119], 0, v[112:113]
	v_or_b32_e32 v2, 60, v116
	global_load_dwordx4 v[112:115], v[112:113], off nt
	v_lshlrev_b64 v[116:117], 13, v[2:3]
	v_lshl_add_u64 v[116:117], v[118:119], 0, v[116:117]
	v_lshl_add_u64 v[94:95], v[118:119], 0, v[94:95]
	v_lshl_add_u64 v[100:101], v[118:119], 0, v[96:97]
	global_load_dwordx4 v[116:119], v[116:117], off nt
	v_add_u32_e32 v2, 0x2cb8, v18
	global_load_dwordx4 v[94:97], v[94:95], off nt
	v_add_u32_e32 v17, 0x30c0, v18
	global_load_dwordx4 v[100:103], v[100:101], off nt
	v_add_u32_e32 v99, 0x30c8, v18
	s_waitcnt vmcnt(15)
	ds_write2_b32 v18, v54, v55 offset1:1
	ds_write2_b32 v18, v56, v57 offset0:2 offset1:3
	s_waitcnt vmcnt(14)
	ds_write2_b32 v31, v58, v59 offset1:1
	ds_write2_b32 v32, v60, v61 offset1:1
	s_waitcnt vmcnt(13)
	ds_write2_b32 v33, v62, v63 offset1:1
	ds_write2_b32 v34, v64, v65 offset1:1
	s_waitcnt vmcnt(12)
	ds_write2_b32 v35, v66, v67 offset1:1
	ds_write2_b32 v36, v68, v69 offset1:1
	s_waitcnt vmcnt(11)
	ds_write2_b32 v37, v70, v71 offset1:1
	ds_write2_b32 v38, v72, v73 offset1:1
	s_waitcnt vmcnt(10)
	ds_write2_b32 v39, v74, v75 offset1:1
	ds_write2_b32 v40, v76, v77 offset1:1
	s_waitcnt vmcnt(9)
	ds_write2_b32 v41, v78, v79 offset1:1
	ds_write2_b32 v42, v80, v81 offset1:1
	s_waitcnt vmcnt(8)
	ds_write2_b32 v43, v82, v83 offset1:1
	ds_write2_b32 v44, v84, v85 offset1:1
	s_waitcnt vmcnt(7)
	ds_write2_b32 v45, v86, v87 offset1:1
	ds_write2_b32 v46, v88, v89 offset1:1
	s_waitcnt vmcnt(6)
	ds_write2_b32 v47, v90, v91 offset1:1
	ds_write2_b32 v48, v92, v93 offset1:1
	s_waitcnt vmcnt(1)
	ds_write2_b32 v49, v94, v95 offset1:1
	ds_write2_b32 v50, v96, v97 offset1:1
	s_waitcnt vmcnt(0)
	ds_write2_b32 v51, v100, v101 offset1:1
	ds_write2_b32 v2, v102, v103 offset1:1
	ds_write2_b32 v17, v104, v105 offset1:1
	ds_write2_b32 v99, v106, v107 offset1:1
	v_add_u32_e32 v2, 0x34d0, v18
	v_add_u32_e32 v62, 0x400, v20
	v_mov_b32_e32 v17, v3
	v_lshl_add_u64 v[16:17], v[16:17], 1, v[6:7]
	ds_write2_b32 v2, v108, v109 offset1:1
	v_add_u32_e32 v2, 0x34d8, v18
	ds_write2_b32 v2, v110, v111 offset1:1
	v_add_u32_e32 v2, 0x38e0, v18
	ds_write2_b32 v2, v112, v113 offset1:1
	v_add_u32_e32 v2, 0x38e8, v18
	ds_write2_b32 v2, v114, v115 offset1:1
	v_add_u32_e32 v2, 0x3cf0, v18
	ds_write2_b32 v2, v116, v117 offset1:1
	v_add_u32_e32 v2, 0x3cf8, v18
	ds_write2_b32 v2, v118, v119 offset1:1
	s_waitcnt lgkmcnt(0)
	ds_read2_b32 v[54:55], v20 offset1:65
	s_waitcnt lgkmcnt(0)
	v_cvt_pk_bf16_f32 v54, v54, v55
	ds_read2_b32 v[56:57], v20 offset0:130 offset1:195
	v_or_b32_e32 v2, v53, v19
	s_waitcnt lgkmcnt(0)
	v_cvt_pk_bf16_f32 v55, v56, v57
	ds_read2_b32 v[56:57], v62 offset0:4 offset1:69
	v_lshlrev_b32_e32 v2, 12, v2
	s_waitcnt lgkmcnt(0)
	v_cvt_pk_bf16_f32 v56, v56, v57
	ds_read2_b32 v[58:59], v62 offset0:134 offset1:199
	s_waitcnt lgkmcnt(0)
	v_cvt_pk_bf16_f32 v57, v58, v59
	v_lshl_add_u64 v[60:61], v[16:17], 0, v[2:3]
	ds_read2_b32 v[58:59], v20 offset0:8 offset1:73
	global_store_dwordx4 v[60:61], v[54:57], off sc0 sc1
	v_or_b32_e32 v2, v53, v21
	v_lshlrev_b32_e32 v2, 12, v2
	s_waitcnt lgkmcnt(0)
	v_cvt_pk_bf16_f32 v54, v58, v59
	ds_read2_b32 v[56:57], v20 offset0:138 offset1:203
	s_waitcnt lgkmcnt(0)
	v_cvt_pk_bf16_f32 v55, v56, v57
	ds_read2_b32 v[56:57], v62 offset0:12 offset1:77
	s_waitcnt lgkmcnt(0)
	v_cvt_pk_bf16_f32 v56, v56, v57
	ds_read2_b32 v[58:59], v62 offset0:142 offset1:207
	s_waitcnt lgkmcnt(0)
	v_cvt_pk_bf16_f32 v57, v58, v59
	v_lshl_add_u64 v[60:61], v[16:17], 0, v[2:3]
	ds_read2_b32 v[58:59], v20 offset0:16 offset1:81
	global_store_dwordx4 v[60:61], v[54:57], off sc0 sc1
	v_or_b32_e32 v2, v53, v22
	v_lshlrev_b32_e32 v2, 12, v2
	s_waitcnt lgkmcnt(0)
	v_cvt_pk_bf16_f32 v54, v58, v59
	ds_read2_b32 v[56:57], v20 offset0:146 offset1:211
	s_waitcnt lgkmcnt(0)
	v_cvt_pk_bf16_f32 v55, v56, v57
	ds_read2_b32 v[56:57], v62 offset0:20 offset1:85
	s_waitcnt lgkmcnt(0)
	v_cvt_pk_bf16_f32 v56, v56, v57
	ds_read2_b32 v[58:59], v62 offset0:150 offset1:215
	s_waitcnt lgkmcnt(0)
	v_cvt_pk_bf16_f32 v57, v58, v59
	v_lshl_add_u64 v[60:61], v[16:17], 0, v[2:3]
	ds_read2_b32 v[58:59], v20 offset0:24 offset1:89
	global_store_dwordx4 v[60:61], v[54:57], off sc0 sc1
	v_or_b32_e32 v2, v53, v23
	v_lshlrev_b32_e32 v2, 12, v2
	s_waitcnt lgkmcnt(0)
	v_cvt_pk_bf16_f32 v54, v58, v59
	ds_read2_b32 v[56:57], v20 offset0:154 offset1:219
	s_waitcnt lgkmcnt(0)
	v_cvt_pk_bf16_f32 v55, v56, v57
	ds_read2_b32 v[56:57], v62 offset0:28 offset1:93
	s_waitcnt lgkmcnt(0)
	v_cvt_pk_bf16_f32 v56, v56, v57
	ds_read2_b32 v[58:59], v62 offset0:158 offset1:223
	s_waitcnt lgkmcnt(0)
	v_cvt_pk_bf16_f32 v57, v58, v59
	v_lshl_add_u64 v[60:61], v[16:17], 0, v[2:3]
	ds_read2_b32 v[58:59], v20 offset0:32 offset1:97
	global_store_dwordx4 v[60:61], v[54:57], off sc0 sc1
	v_or_b32_e32 v2, v53, v24
	v_lshlrev_b32_e32 v2, 12, v2
	s_waitcnt lgkmcnt(0)
	v_cvt_pk_bf16_f32 v54, v58, v59
	ds_read2_b32 v[56:57], v20 offset0:162 offset1:227
	s_waitcnt lgkmcnt(0)
	v_cvt_pk_bf16_f32 v55, v56, v57
	ds_read2_b32 v[56:57], v62 offset0:36 offset1:101
	s_waitcnt lgkmcnt(0)
	v_cvt_pk_bf16_f32 v56, v56, v57
	ds_read2_b32 v[58:59], v62 offset0:166 offset1:231
	s_waitcnt lgkmcnt(0)
	v_cvt_pk_bf16_f32 v57, v58, v59
	v_lshl_add_u64 v[60:61], v[16:17], 0, v[2:3]
	ds_read2_b32 v[58:59], v20 offset0:40 offset1:105
	global_store_dwordx4 v[60:61], v[54:57], off sc0 sc1
	v_or_b32_e32 v2, v53, v25
	v_lshlrev_b32_e32 v2, 12, v2
	s_waitcnt lgkmcnt(0)
	v_cvt_pk_bf16_f32 v54, v58, v59
	ds_read2_b32 v[56:57], v20 offset0:170 offset1:235
	s_waitcnt lgkmcnt(0)
	v_cvt_pk_bf16_f32 v55, v56, v57
	ds_read2_b32 v[56:57], v62 offset0:44 offset1:109
	s_waitcnt lgkmcnt(0)
	v_cvt_pk_bf16_f32 v56, v56, v57
	ds_read2_b32 v[58:59], v62 offset0:174 offset1:239
	s_waitcnt lgkmcnt(0)
	v_cvt_pk_bf16_f32 v57, v58, v59
	v_lshl_add_u64 v[60:61], v[16:17], 0, v[2:3]
	ds_read2_b32 v[58:59], v20 offset0:48 offset1:113
	global_store_dwordx4 v[60:61], v[54:57], off sc0 sc1
	v_or_b32_e32 v2, v53, v26
	v_lshlrev_b32_e32 v2, 12, v2
	s_waitcnt lgkmcnt(0)
	v_cvt_pk_bf16_f32 v54, v58, v59
	ds_read2_b32 v[56:57], v20 offset0:178 offset1:243
	s_waitcnt lgkmcnt(0)
	v_cvt_pk_bf16_f32 v55, v56, v57
	ds_read2_b32 v[56:57], v62 offset0:52 offset1:117
	s_waitcnt lgkmcnt(0)
	v_cvt_pk_bf16_f32 v56, v56, v57
	ds_read2_b32 v[58:59], v62 offset0:182 offset1:247
	s_waitcnt lgkmcnt(0)
	v_cvt_pk_bf16_f32 v57, v58, v59
	v_lshl_add_u64 v[60:61], v[16:17], 0, v[2:3]
	v_or_b32_e32 v2, v53, v27
	ds_read2_b32 v[58:59], v20 offset0:56 offset1:121
	global_store_dwordx4 v[60:61], v[54:57], off sc0 sc1
	v_lshlrev_b32_e32 v2, 12, v2
	v_lshl_add_u64 v[16:17], v[16:17], 0, v[2:3]
	s_waitcnt lgkmcnt(0)
	v_cvt_pk_bf16_f32 v54, v58, v59
	ds_read2_b32 v[56:57], v20 offset0:186 offset1:251
	s_waitcnt lgkmcnt(0)
	v_cvt_pk_bf16_f32 v55, v56, v57
	ds_read2_b32 v[56:57], v62 offset0:60 offset1:125
	s_waitcnt lgkmcnt(0)
	v_cvt_pk_bf16_f32 v56, v56, v57
	ds_read2_b32 v[58:59], v62 offset0:190 offset1:255
	s_waitcnt lgkmcnt(0)
	v_cvt_pk_bf16_f32 v57, v58, v59
	global_store_dwordx4 v[16:17], v[54:57], off sc0 sc1
	s_waitcnt lgkmcnt(0)

.LBB0_58:
	s_or_b64 exec, exec, s[0:1]
	s_waitcnt vmcnt(0)
	v_mul_f32_e32 v100, v35, v35
	v_mul_f32_e32 v106, v37, v37
	v_fmac_f32_e32 v100, v34, v34
	v_fmac_f32_e32 v106, v36, v36
	v_add_f32_e32 v100, v100, v106
	v_mul_f32_e32 v106, v43, v43
	v_mul_f32_e32 v107, v45, v45
	v_fmac_f32_e32 v106, v42, v42
	v_fmac_f32_e32 v107, v44, v44
	v_add_f32_e32 v106, v106, v107
	v_mul_f32_e32 v107, v39, v39
	v_mul_f32_e32 v117, v41, v41
	v_fmac_f32_e32 v107, v38, v38
	v_fmac_f32_e32 v117, v40, v40
	v_add_f32_e32 v107, v107, v117
	v_add_f32_e32 v100, v100, v107
	v_mul_f32_e32 v107, v51, v51
	v_mul_f32_e32 v117, v53, v53
	v_fmac_f32_e32 v107, v50, v50
	v_fmac_f32_e32 v117, v52, v52
	v_add_f32_e32 v107, v107, v117
	v_add_f32_e32 v106, v106, v107
	v_mul_f32_e32 v107, v47, v47
	v_mul_f32_e32 v117, v49, v49
	v_fmac_f32_e32 v107, v46, v46
	v_fmac_f32_e32 v117, v48, v48
	v_add_f32_e32 v107, v107, v117
	v_add_f32_e32 v100, v100, v107
	v_mul_f32_e32 v107, v59, v59
	v_mul_f32_e32 v117, v61, v61
	v_fmac_f32_e32 v107, v58, v58
	v_fmac_f32_e32 v117, v60, v60
	v_add_f32_e32 v107, v107, v117
	v_add_f32_e32 v106, v106, v107
	v_mul_f32_e32 v107, v55, v55
	v_mul_f32_e32 v117, v57, v57
	v_fmac_f32_e32 v107, v54, v54
	v_fmac_f32_e32 v117, v56, v56
	v_add_f32_e32 v107, v107, v117
	v_add_f32_e32 v100, v100, v107
	v_mul_f32_e32 v107, v67, v67
	v_mul_f32_e32 v117, v69, v69
	v_fmac_f32_e32 v107, v66, v66
	v_fmac_f32_e32 v117, v68, v68
	v_add_f32_e32 v107, v107, v117
	v_add_f32_e32 v106, v106, v107
	v_mul_f32_e32 v107, v63, v63
	v_mul_f32_e32 v117, v65, v65
	v_fmac_f32_e32 v107, v62, v62
	v_fmac_f32_e32 v117, v64, v64
	v_add_f32_e32 v107, v107, v117
	v_add_f32_e32 v100, v100, v107
	v_mul_f32_e32 v107, v71, v71
	v_mul_f32_e32 v117, v73, v73
	v_fmac_f32_e32 v107, v70, v70
	v_fmac_f32_e32 v117, v72, v72
	v_add_f32_e32 v107, v107, v117
	v_add_f32_e32 v100, v100, v107
	v_mul_f32_e32 v107, v79, v79
	v_mul_f32_e32 v117, v81, v81
	v_fmac_f32_e32 v107, v78, v78
	v_fmac_f32_e32 v117, v80, v80
	v_add_f32_e32 v107, v107, v117
	v_add_f32_e32 v100, v100, v107
	v_mul_f32_e32 v107, v87, v87
	v_mul_f32_e32 v117, v89, v89
	v_fmac_f32_e32 v107, v86, v86
	v_fmac_f32_e32 v117, v88, v88
	v_add_f32_e32 v107, v107, v117
	v_add_f32_e32 v100, v100, v107
	ds_bpermute_b32 v107, v1, v100
	v_mul_f32_e32 v117, v75, v75
	v_mul_f32_e32 v118, v77, v77
	v_fmac_f32_e32 v117, v74, v74
	v_fmac_f32_e32 v118, v76, v76
	s_waitcnt lgkmcnt(0)
	v_add_f32_e32 v100, v100, v107
	ds_bpermute_b32 v107, v108, v100
	v_add_f32_e32 v117, v117, v118
	v_add_f32_e32 v106, v106, v117
	v_mul_f32_e32 v117, v83, v83
	v_mul_f32_e32 v118, v85, v85
	v_fmac_f32_e32 v117, v82, v82
	v_fmac_f32_e32 v118, v84, v84
	s_waitcnt lgkmcnt(0)
	v_add_f32_e32 v100, v100, v107
	v_add_f32_e32 v117, v117, v118
	ds_bpermute_b32 v107, v109, v100
	v_add_f32_e32 v106, v106, v117
	v_mul_f32_e32 v117, v91, v91
	v_mul_f32_e32 v118, v93, v93
	v_fmac_f32_e32 v117, v90, v90
	v_fmac_f32_e32 v118, v92, v92
	v_add_f32_e32 v117, v117, v118
	v_add_f32_e32 v106, v106, v117
	v_mul_f32_e32 v117, v95, v95
	v_mul_f32_e32 v118, v97, v97
	v_fmac_f32_e32 v117, v94, v94
	v_fmac_f32_e32 v118, v96, v96
	s_waitcnt lgkmcnt(0)
	v_add_f32_e32 v100, v100, v107
	v_add_f32_e32 v117, v117, v118
	ds_bpermute_b32 v107, v110, v100
	v_add_f32_e32 v106, v106, v117
	ds_bpermute_b32 v117, v1, v106
	v_lshlrev_b64 v[98:99], 12, v[98:99]
	s_waitcnt lgkmcnt(1)
	v_add_f32_e32 v100, v100, v107
	ds_bpermute_b32 v107, v111, v100
	s_waitcnt lgkmcnt(1)
	v_add_f32_e32 v106, v106, v117
	ds_bpermute_b32 v117, v108, v106
	s_waitcnt lgkmcnt(1)
	v_add_f32_e32 v100, v100, v107
	ds_bpermute_b32 v107, v112, v100
	s_waitcnt lgkmcnt(1)
	v_add_f32_e32 v106, v106, v117
	ds_bpermute_b32 v117, v109, v106
	s_waitcnt lgkmcnt(1)
	v_add_f32_e32 v100, v100, v107
	v_fmamk_f32 v100, v100, 0x3a000000, v113
	s_waitcnt lgkmcnt(0)
	v_add_f32_e32 v106, v106, v117
	v_mul_f32_e32 v107, 0x4f800000, v100
	v_cmp_gt_f32_e32 vcc, s13, v100
	ds_bpermute_b32 v117, v110, v106
	s_waitcnt lgkmcnt(0)
	v_add_f32_e32 v106, v106, v117
	v_cndmask_b32_e32 v100, v100, v107, vcc
	v_sqrt_f32_e32 v107, v100
	ds_bpermute_b32 v117, v111, v106
	v_add_u32_e32 v118, -1, v107
	v_fma_f32 v119, -v118, v107, v100
	v_cmp_ge_f32_e64 s[6:7], 0, v119
	v_add_u32_e32 v119, 1, v107
	s_waitcnt lgkmcnt(0)
	v_add_f32_e32 v106, v106, v117
	v_cndmask_b32_e64 v118, v107, v118, s[6:7]
	v_fma_f32 v107, -v119, v107, v100
	v_cmp_lt_f32_e64 s[6:7], 0, v107
	ds_bpermute_b32 v117, v112, v106
	s_waitcnt lgkmcnt(0)
	v_add_f32_e32 v106, v106, v117
	v_cndmask_b32_e64 v107, v118, v119, s[6:7]
	v_mul_f32_e32 v118, 0x37800000, v107
	v_cndmask_b32_e32 v107, v107, v118, vcc
	v_cmp_class_f32_e32 vcc, v100, v114
	v_fmamk_f32 v106, v106, 0x3a000000, v113
	v_mul_f32_e32 v117, 0x4f800000, v106
	v_cndmask_b32_e32 v100, v107, v100, vcc
	v_div_scale_f32 v107, s[0:1], v100, v100, 1.0
	v_rcp_f32_e32 v118, v107
	v_cmp_gt_f32_e64 s[6:7], s13, v106
	v_fma_f32 v119, -v107, v118, 1.0
	s_nop 0
	v_cndmask_b32_e64 v106, v106, v117, s[6:7]
	v_fmac_f32_e32 v118, v119, v118
	v_div_scale_f32 v119, vcc, 1.0, v100, 1.0
	v_sqrt_f32_e32 v117, v106
	v_mul_f32_e32 v120, v119, v118
	v_fma_f32 v121, -v107, v120, v119
	v_fmac_f32_e32 v120, v121, v118
	v_fma_f32 v107, -v107, v120, v119
	v_add_u32_e32 v119, -1, v117
	v_fma_f32 v121, -v119, v117, v106
	v_cmp_ge_f32_e64 s[8:9], 0, v121
	v_add_u32_e32 v121, 1, v117
	v_div_fmas_f32 v107, v107, v118, v120
	v_cndmask_b32_e64 v119, v117, v119, s[8:9]
	v_fma_f32 v117, -v121, v117, v106
	v_cmp_lt_f32_e64 s[8:9], 0, v117
	s_nop 1
	v_cndmask_b32_e64 v117, v119, v121, s[8:9]
	v_mul_f32_e32 v119, 0x37800000, v117
	v_cndmask_b32_e64 v117, v117, v119, s[6:7]
	v_cmp_class_f32_e64 s[6:7], v106, v114
	s_nop 1
	v_cndmask_b32_e64 v106, v117, v106, s[6:7]
	v_div_scale_f32 v119, s[0:1], v106, v106, 1.0
	v_rcp_f32_e32 v121, v119
	v_div_fixup_f32 v117, v107, v100, 1.0
	v_mul_f32_e32 v34, v34, v117
	v_mul_f32_e32 v35, v35, v117
	v_fma_f32 v100, -v119, v121, 1.0
	v_fmac_f32_e32 v121, v100, v121
	v_div_scale_f32 v100, vcc, 1.0, v106, 1.0
	v_mul_f32_e32 v107, v100, v121
	v_fma_f32 v118, -v119, v107, v100
	v_fmac_f32_e32 v107, v118, v121
	v_fma_f32 v100, -v119, v107, v100
	v_div_fmas_f32 v100, v100, v121, v107
	v_mul_f32_e32 v34, v30, v34
	v_mul_f32_e32 v35, v31, v35
	v_div_fixup_f32 v100, v100, v106, 1.0
	v_lshl_add_u64 v[106:107], v[102:103], 0, v[98:99]
	v_lshlrev_b64 v[98:99], 12, v[104:105]
	v_cvt_pk_bf16_f32 v34, v34, v35
	v_mul_f32_e32 v35, v36, v117
	v_lshl_add_u64 v[98:99], v[102:103], 0, v[98:99]
	v_cmp_gt_i32_e32 vcc, s2, v104
	v_mul_f32_e32 v35, v32, v35
	v_mul_f32_e32 v36, v37, v117
	v_mul_f32_e32 v36, v33, v36
	v_cvt_pk_bf16_f32 v35, v35, v36
	global_store_dwordx2 v[106:107], v[34:35], off sc0 sc1
	s_and_saveexec_b64 s[0:1], vcc
	s_cbranch_execz .LBB0_60
	v_mul_f32_e32 v34, v42, v100
	v_mul_f32_e32 v35, v43, v100
	v_mul_f32_e32 v34, v30, v34
	v_mul_f32_e32 v35, v31, v35
	v_cvt_pk_bf16_f32 v34, v34, v35
	v_mul_f32_e32 v35, v44, v100
	v_mul_f32_e32 v35, v32, v35
	v_mul_f32_e32 v36, v45, v100
	v_mul_f32_e32 v36, v33, v36
	v_cvt_pk_bf16_f32 v35, v35, v36
	global_store_dwordx2 v[98:99], v[34:35], off sc0 sc1
.LBB0_60:
	s_or_b64 exec, exec, s[0:1]
	v_mul_f32_e32 v34, v38, v117
	v_mul_f32_e32 v35, v39, v117
	v_mul_f32_e32 v34, v26, v34
	v_mul_f32_e32 v35, v27, v35
	v_cvt_pk_bf16_f32 v34, v34, v35
	v_mul_f32_e32 v35, v40, v117
	v_mul_f32_e32 v35, v28, v35
	v_mul_f32_e32 v36, v41, v117
	v_mul_f32_e32 v36, v29, v36
	v_cvt_pk_bf16_f32 v35, v35, v36
	global_store_dwordx2 v[106:107], v[34:35], off offset:512 sc0 sc1
	s_and_saveexec_b64 s[0:1], vcc
	s_cbranch_execz .LBB0_62
	v_mul_f32_e32 v34, v50, v100
	v_mul_f32_e32 v35, v51, v100
	v_mul_f32_e32 v34, v26, v34
	v_mul_f32_e32 v35, v27, v35
	v_cvt_pk_bf16_f32 v34, v34, v35
	v_mul_f32_e32 v35, v52, v100
	v_mul_f32_e32 v35, v28, v35
	v_mul_f32_e32 v36, v53, v100
	v_mul_f32_e32 v36, v29, v36
	v_cvt_pk_bf16_f32 v35, v35, v36
	global_store_dwordx2 v[98:99], v[34:35], off offset:512 sc0 sc1
.LBB0_62:
	s_or_b64 exec, exec, s[0:1]
	v_mul_f32_e32 v34, v46, v117
	v_mul_f32_e32 v35, v47, v117
	v_mul_f32_e32 v34, v22, v34
	v_mul_f32_e32 v35, v23, v35
	v_cvt_pk_bf16_f32 v34, v34, v35
	v_mul_f32_e32 v35, v48, v117
	v_mul_f32_e32 v35, v24, v35
	v_mul_f32_e32 v36, v49, v117
	v_mul_f32_e32 v36, v25, v36
	v_cvt_pk_bf16_f32 v35, v35, v36
	global_store_dwordx2 v[106:107], v[34:35], off offset:1024 sc0 sc1
	s_and_saveexec_b64 s[0:1], vcc
	s_cbranch_execz .LBB0_64
	v_mul_f32_e32 v34, v58, v100
	v_mul_f32_e32 v35, v59, v100
	v_mul_f32_e32 v34, v22, v34
	v_mul_f32_e32 v35, v23, v35
	v_cvt_pk_bf16_f32 v34, v34, v35
	v_mul_f32_e32 v35, v60, v100
	v_mul_f32_e32 v35, v24, v35
	v_mul_f32_e32 v36, v61, v100
	v_mul_f32_e32 v36, v25, v36
	v_cvt_pk_bf16_f32 v35, v35, v36
	global_store_dwordx2 v[98:99], v[34:35], off offset:1024 sc0 sc1
.LBB0_64:
	s_or_b64 exec, exec, s[0:1]
	v_mul_f32_e32 v34, v54, v117
	v_mul_f32_e32 v35, v55, v117
	v_mul_f32_e32 v34, v18, v34
	v_mul_f32_e32 v35, v19, v35
	v_cvt_pk_bf16_f32 v34, v34, v35
	v_mul_f32_e32 v35, v56, v117
	v_mul_f32_e32 v35, v20, v35
	v_mul_f32_e32 v36, v57, v117
	v_mul_f32_e32 v36, v21, v36
	v_cvt_pk_bf16_f32 v35, v35, v36
	global_store_dwordx2 v[106:107], v[34:35], off offset:1536 sc0 sc1
	s_and_saveexec_b64 s[0:1], vcc
	s_cbranch_execz .LBB0_66
	v_mul_f32_e32 v34, v66, v100
	v_mul_f32_e32 v35, v67, v100
	v_mul_f32_e32 v34, v18, v34
	v_mul_f32_e32 v35, v19, v35
	v_cvt_pk_bf16_f32 v34, v34, v35
	v_mul_f32_e32 v35, v68, v100
	v_mul_f32_e32 v35, v20, v35
	v_mul_f32_e32 v36, v69, v100
	v_mul_f32_e32 v36, v21, v36
	v_cvt_pk_bf16_f32 v35, v35, v36
	global_store_dwordx2 v[98:99], v[34:35], off offset:1536 sc0 sc1
.LBB0_66:
	s_or_b64 exec, exec, s[0:1]
	v_mul_f32_e32 v34, v62, v117
	v_mul_f32_e32 v35, v63, v117
	v_mul_f32_e32 v34, v14, v34
	v_mul_f32_e32 v35, v15, v35
	v_cvt_pk_bf16_f32 v34, v34, v35
	v_mul_f32_e32 v35, v64, v117
	v_mul_f32_e32 v35, v16, v35
	v_mul_f32_e32 v36, v65, v117
	v_mul_f32_e32 v36, v17, v36
	v_cvt_pk_bf16_f32 v35, v35, v36
	global_store_dwordx2 v[106:107], v[34:35], off offset:2048 sc0 sc1
	s_and_saveexec_b64 s[0:1], vcc
	s_cbranch_execz .LBB0_68
	v_mul_f32_e32 v34, v74, v100
	v_mul_f32_e32 v35, v75, v100
	v_mul_f32_e32 v34, v14, v34
	v_mul_f32_e32 v35, v15, v35
	v_cvt_pk_bf16_f32 v34, v34, v35
	v_mul_f32_e32 v35, v76, v100
	v_mul_f32_e32 v35, v16, v35
	v_mul_f32_e32 v36, v77, v100
	v_mul_f32_e32 v36, v17, v36
	v_cvt_pk_bf16_f32 v35, v35, v36
	global_store_dwordx2 v[98:99], v[34:35], off offset:2048 sc0 sc1
.LBB0_68:
	s_or_b64 exec, exec, s[0:1]
	v_mul_f32_e32 v34, v70, v117
	v_mul_f32_e32 v35, v71, v117
	v_mul_f32_e32 v34, v10, v34
	v_mul_f32_e32 v35, v11, v35
	v_cvt_pk_bf16_f32 v34, v34, v35
	v_mul_f32_e32 v35, v72, v117
	v_mul_f32_e32 v35, v12, v35
	v_mul_f32_e32 v36, v73, v117
	v_mul_f32_e32 v36, v13, v36
	v_cvt_pk_bf16_f32 v35, v35, v36
	global_store_dwordx2 v[106:107], v[34:35], off offset:2560 sc0 sc1
	s_and_saveexec_b64 s[0:1], vcc
	s_cbranch_execz .LBB0_70
	v_mul_f32_e32 v34, v82, v100
	v_mul_f32_e32 v35, v83, v100
	v_mul_f32_e32 v34, v10, v34
	v_mul_f32_e32 v35, v11, v35
	v_cvt_pk_bf16_f32 v34, v34, v35
	v_mul_f32_e32 v35, v84, v100
	v_mul_f32_e32 v35, v12, v35
	v_mul_f32_e32 v36, v85, v100
	v_mul_f32_e32 v36, v13, v36
	v_cvt_pk_bf16_f32 v35, v35, v36
	global_store_dwordx2 v[98:99], v[34:35], off offset:2560 sc0 sc1
.LBB0_70:
	s_or_b64 exec, exec, s[0:1]
	v_mul_f32_e32 v34, v78, v117
	v_mul_f32_e32 v35, v79, v117
	v_mul_f32_e32 v34, v6, v34
	v_mul_f32_e32 v35, v7, v35
	v_cvt_pk_bf16_f32 v34, v34, v35
	v_mul_f32_e32 v35, v80, v117
	v_mul_f32_e32 v35, v8, v35
	v_mul_f32_e32 v36, v81, v117
	v_mul_f32_e32 v36, v9, v36
	v_cvt_pk_bf16_f32 v35, v35, v36
	global_store_dwordx2 v[106:107], v[34:35], off offset:3072 sc0 sc1
	s_and_saveexec_b64 s[0:1], vcc
	s_cbranch_execz .LBB0_72
	v_mul_f32_e32 v34, v90, v100
	v_mul_f32_e32 v35, v91, v100
	v_mul_f32_e32 v34, v6, v34
	v_mul_f32_e32 v35, v7, v35
	v_cvt_pk_bf16_f32 v34, v34, v35
	v_mul_f32_e32 v35, v92, v100
	v_mul_f32_e32 v35, v8, v35
	v_mul_f32_e32 v36, v93, v100
	v_mul_f32_e32 v36, v9, v36
	v_cvt_pk_bf16_f32 v35, v35, v36
	global_store_dwordx2 v[98:99], v[34:35], off offset:3072 sc0 sc1
.LBB0_72:
	s_or_b64 exec, exec, s[0:1]
	v_mul_f32_e32 v34, v86, v117
	v_mul_f32_e32 v35, v87, v117
	v_mul_f32_e32 v34, v2, v34
	v_mul_f32_e32 v35, v3, v35
	v_cvt_pk_bf16_f32 v34, v34, v35
	v_mul_f32_e32 v35, v88, v117
	v_mul_f32_e32 v35, v4, v35
	v_mul_f32_e32 v36, v89, v117
	v_mul_f32_e32 v36, v5, v36
	v_cvt_pk_bf16_f32 v35, v35, v36
	global_store_dwordx2 v[106:107], v[34:35], off offset:3584 sc0 sc1
	s_and_saveexec_b64 s[0:1], vcc
	s_cbranch_execz .LBB0_25
	v_mul_f32_e32 v34, v94, v100
	v_mul_f32_e32 v35, v95, v100
	v_mul_f32_e32 v34, v2, v34
	v_mul_f32_e32 v35, v3, v35
	v_cvt_pk_bf16_f32 v34, v34, v35
	v_mul_f32_e32 v35, v96, v100
	v_mul_f32_e32 v35, v4, v35
	v_mul_f32_e32 v36, v97, v100
	v_mul_f32_e32 v36, v5, v36
	v_cvt_pk_bf16_f32 v35, v35, v36
	global_store_dwordx2 v[98:99], v[34:35], off offset:3584 sc0 sc1
	s_branch .LBB0_25
